# NA latent tile: branch-free bias+mask (ds_read2 + bfe/bfi) instead of 16 divergent ds_read blocks
# speedup vs baseline: 1.0078x; 1.0078x over previous
; DI f32x16 mfma32(bf16x8 a, bf16x8 b, f32x16 c) { return __builtin_amdgcn_mfma_f32_32x32x16_bf16(a, b, c, 0, 0, 0); }
; DI float xmax32(float x) { auto r = __builtin_amdgcn_permlane32_swap(__float_as_uint(x), __float_as_uint(x), false, false); return fmaxf(__uint_as_float(r[0]), __uint_as_float(r[1])); }
; template <int NB>
; DI void softmax_pv(f32x16 (&s)[2], float& mrun, float& lsum, f32x16 (&O)[2], unsigned vaddr) {
;     ...
;   if (NB == 2) tr_read_vtile(vf, vaddr);
;   else tr_read_vtile8(vf8, vaddr);
;   float mx = -1e30f;
; #pragma unroll
;   for (int kb = 0; kb < NB; ++kb)
; #pragma unroll
;     for (int e = 0; e < 16; ++e) mx = fmaxf(mx, s[kb][e]);
;   mx = xmax32(mx);
;   constexpr float THR = 8.f;
;   float alpha = 1.f;
;   if (__builtin_amdgcn_ballot_w64(mx - mrun > THR) != 0ull) {
;     const float mnew = fmaxf(mrun, mx);
;     alpha = __builtin_amdgcn_exp2f((mrun - mnew) * L2E);
;     mrun = mnew;
; #pragma unroll
;     for (int e = 0; e < 16; ++e) { O[0][e] *= alpha; O[1][e] *= alpha; }
; template <int kind>
; __device__ void attn_job(const Params& p, int layer, int idx, char* smem) {
;     ...
;       const int kr = R0 + i - 4;
;       if (kr >= r0A && kr < r0A + 9) {
;         f32x16 s[2];
; #pragma unroll
;         for (int st = 0; st < 4; ++st) s[0] = mfma32(ld_frag16(Kb + (k0 + tq) * KS_STRIDE + 16 * st + 8 * hh), qf[st], st == 0 ? zero16 : s[0]);
;         const bool rowvalid = (kr >= r0l) && (kr < r0l + 8);
;         const unsigned m = rowvalid ? colmask : 0u;
;         const float* brow = rpbs + (kr - qrow_l + 7) * 32 + dcbase;
; #pragma unroll
;         for (int e = 0; e < 16; ++e) {
;           const float bias = brow[(e & 3) + 8 * (e >> 2)];
;           s[0][e] = ((m >> e) & 1u) ? s[0][e] + bias : -1e30f;
;         }
;         softmax_pv<1>(s, mrun, lsum, O, (unsigned)(size_t)Vb + vlane_off + (unsigned)(k0 * KS_STRIDE * 2));
.LBB0_475:
	s_add_i32 s0, s11, s13
	s_cmp_ge_i32 s0, s6
	s_cselect_b64 s[16:17], -1, 0
	s_cmp_lt_i32 s0, s10
	s_cselect_b64 s[20:21], -1, 0
	s_and_b64 s[16:17], s[16:17], s[20:21]
	s_andn2_b64 vcc, exec, s[16:17]
	s_cbranch_vccnz .LBB0_512
	v_add3_u32 v0, s14, v185, v180
	ds_read_b128 v[2:5], v0
	v_cmp_ge_i32_e32 vcc, s0, v184
	v_cmp_lt_i32_e64 s[0:1], s0, v186
	s_and_b64 vcc, vcc, s[0:1]
	v_mov_b32_e32 v15, 0xf149f2ca
	v_mov_b32_e32 v14, 0xf149f2ca
	s_waitcnt lgkmcnt(0)
	v_mfma_f32_32x32x16_bf16 v[64:79], v[2:5], v[136:139], v[16:31]
	ds_read_b128 v[2:5], v0 offset:32
	s_waitcnt lgkmcnt(0)
	v_mfma_f32_32x32x16_bf16 v[64:79], v[2:5], v[128:131], v[64:79]
	ds_read_b128 v[2:5], v0 offset:64
	s_waitcnt lgkmcnt(0)
	v_mfma_f32_32x32x16_bf16 v[64:79], v[2:5], v[132:135], v[64:79]
	ds_read_b128 v[2:5], v0 offset:96
	v_cndmask_b32_e32 v0, 0, v179, vcc
	s_waitcnt lgkmcnt(0)
	v_mfma_f32_32x32x16_bf16 v[64:79], v[2:5], v[140:143], v[64:79]
	ds_read2_b32 v[80:81], v189 offset0:2 offset1:3
	ds_read2_b32 v[82:83], v189 offset0:8 offset1:9
	ds_read2_b32 v[6:7], v189 offset0:16 offset1:17
	ds_read2_b32 v[8:9], v189 offset0:18 offset1:19
	ds_read2_b32 v[10:11], v189 offset0:24 offset1:25
	ds_read2_b32 v[12:13], v189 offset0:26 offset1:27
	ds_read2_b32 v[2:3], v189 offset1:1
	ds_read2_b32 v[4:5], v189 offset0:10 offset1:11
	s_waitcnt lgkmcnt(0)
	s_nop 2
	v_pk_add_f32 v[2:3], v[64:65], v[2:3]
	v_pk_add_f32 v[80:81], v[66:67], v[80:81]
	v_pk_add_f32 v[82:83], v[68:69], v[82:83]
	v_pk_add_f32 v[4:5], v[70:71], v[4:5]
	v_pk_add_f32 v[6:7], v[72:73], v[6:7]
	v_pk_add_f32 v[8:9], v[74:75], v[8:9]
	v_pk_add_f32 v[10:11], v[76:77], v[10:11]
	v_pk_add_f32 v[12:13], v[78:79], v[12:13]
	v_bfe_i32 v64, v0, 0, 1
	v_bfe_i32 v65, v0, 1, 1
	v_bfe_i32 v66, v0, 2, 1
	v_bfe_i32 v67, v0, 3, 1
	v_bfi_b32 v14, v64, v2, s24
	v_bfi_b32 v15, v65, v3, s24
	v_bfi_b32 v80, v66, v80, s24
	v_bfi_b32 v81, v67, v81, s24
	v_bfe_i32 v64, v0, 4, 1
	v_bfe_i32 v65, v0, 5, 1
	v_bfe_i32 v66, v0, 6, 1
	v_bfe_i32 v67, v0, 7, 1
	v_bfi_b32 v82, v64, v82, s24
	v_bfi_b32 v83, v65, v83, s24
	v_bfi_b32 v68, v66, v4, s24
	v_bfi_b32 v69, v67, v5, s24
	v_bfe_i32 v64, v0, 8, 1
	v_bfe_i32 v65, v0, 9, 1
	v_bfe_i32 v66, v0, 10, 1
	v_bfe_i32 v67, v0, 11, 1
	v_bfi_b32 v70, v64, v6, s24
	v_bfi_b32 v71, v65, v7, s24
	v_bfi_b32 v72, v66, v8, s24
	v_bfi_b32 v73, v67, v9, s24
	v_bfe_i32 v64, v0, 12, 1
	v_bfe_i32 v65, v0, 13, 1
	v_bfe_i32 v66, v0, 14, 1
	v_bfe_i32 v67, v0, 15, 1
	v_bfi_b32 v74, v64, v10, s24
	v_bfi_b32 v75, v65, v11, s24
	v_bfi_b32 v76, v66, v12, s24
	v_bfi_b32 v77, v67, v13, s24
	v_add_u32_e32 v0, s3, v187
	ds_read_b64_tr_b16 v[64:65], v0 offset:0
	ds_read_b64_tr_b16 v[66:67], v0 offset:1152
	ds_read_b64_tr_b16 v[10:11], v0 offset:64
	ds_read_b64_tr_b16 v[12:13], v0 offset:1216
	ds_read_b64_tr_b16 v[6:7], v0 offset:2304
	ds_read_b64_tr_b16 v[8:9], v0 offset:3456
	ds_read_b64_tr_b16 v[2:3], v0 offset:2368
	ds_read_b64_tr_b16 v[4:5], v0 offset:3520
	s_waitcnt lgkmcnt(0)
	v_max3_f32 v0, v14, s24, v15
	v_max3_f32 v0, v0, v80, v81
	v_max3_f32 v0, v0, v82, v83
	v_max3_f32 v0, v0, v68, v69
	v_max3_f32 v0, v0, v70, v71
	v_max3_f32 v0, v0, v72, v73
	v_max3_f32 v0, v0, v74, v75
	v_max3_f32 v0, v0, v76, v77
	v_mov_b32_e32 v78, v0
	s_nop 1
	v_permlane32_swap_b32_e32 v0, v78
	v_max_f32_e32 v78, v78, v78
	v_max_f32_e32 v0, v0, v0
	v_max_f32_e32 v0, v0, v78
	v_sub_f32_e32 v78, v0, v193
	v_cmp_lt_f32_e32 vcc, s25, v78
	s_cbranch_vccz .LBB0_510
	v_max_f32_e32 v0, v0, v0
	v_max_f32_e32 v78, v193, v193
	v_max_f32_e32 v78, v78, v0
	v_sub_f32_e32 v0, v193, v78
	v_mul_f32_e32 v0, 0x3fb8aa3b, v0
	v_exp_f32_e32 v0, v0
	v_mov_b32_e32 v193, v78
	v_pk_mul_f32 v[46:47], v[46:47], v[0:1] op_sel_hi:[1,0]
	v_pk_mul_f32 v[44:45], v[44:45], v[0:1] op_sel_hi:[1,0]
	v_pk_mul_f32 v[42:43], v[42:43], v[0:1] op_sel_hi:[1,0]
	v_pk_mul_f32 v[40:41], v[40:41], v[0:1] op_sel_hi:[1,0]
	v_pk_mul_f32 v[38:39], v[38:39], v[0:1] op_sel_hi:[1,0]
	v_pk_mul_f32 v[36:37], v[36:37], v[0:1] op_sel_hi:[1,0]
	v_pk_mul_f32 v[34:35], v[34:35], v[0:1] op_sel_hi:[1,0]
	v_pk_mul_f32 v[32:33], v[32:33], v[0:1] op_sel_hi:[1,0]
	v_pk_mul_f32 v[62:63], v[62:63], v[0:1] op_sel_hi:[1,0]
	v_pk_mul_f32 v[60:61], v[60:61], v[0:1] op_sel_hi:[1,0]
	v_pk_mul_f32 v[58:59], v[58:59], v[0:1] op_sel_hi:[1,0]
	v_pk_mul_f32 v[56:57], v[56:57], v[0:1] op_sel_hi:[1,0]
	v_pk_mul_f32 v[54:55], v[54:55], v[0:1] op_sel_hi:[1,0]
	v_pk_mul_f32 v[52:53], v[52:53], v[0:1] op_sel_hi:[1,0]
	v_pk_mul_f32 v[50:51], v[50:51], v[0:1] op_sel_hi:[1,0]
	v_pk_mul_f32 v[48:49], v[48:49], v[0:1] op_sel_hi:[1,0]
	s_branch .LBB0_511
